# v46 + ffn1_out(L0) latent tile order transposed inside each XCD's 8-panel group (4 panels x 8 column tiles per round, A panels streamed once)
# speedup vs baseline: 1.0017x; 1.0017x over previous
;     __host__ __device__ __forceinline__ bool next(int i, Unit& u) const {
;         const long L = (long)i * G + c; if (L >= nwg) return false;
;         int wgid = (int)L; { const int q = nwg / NXCD, r = nwg % NXCD, xcd = wgid % NXCD, off = wgid / NXCD; wgid = (xcd < r ? xcd * (q + 1) : r * (q + 1) + (xcd - r) * q) + off; }
;         const int nig = WGM * nN, gid = wgid / nig, fm = gid * WGM, gsz = (nM - fm) < WGM ? (nM - fm) : WGM;
;         u.pm = fm + ((wgid % nig) % gsz); u.pn = (wgid % nig) / gsz; u.ko = 0; u.nk = nk; return true;
;     }
; template <class Epi, class Sched, bool ALIGN_EPI = false, bool SP2 = false>
; __device__ __forceinline__ void gemm_phase(PG8_LAS unsigned char* lds, const Gemm g, const Sched& S, const Epi& E, const int wv) {
;     ...
;     Unit cur, nxt; int ui = 0;
;     ...
;     bool ok0_; cur.pm = 0; cur.pn = 0; cur.ko = 0; cur.nk = 4; cur.ks = 0; PG8_NEXT(0, cur, ok0_);
;     if (!ok0_) return;
;     f32x4 acc[2][2][4][2];
; #pragma unroll
;     for (int a = 0; a < 2; ++a)
; #pragma unroll
;         for (int b = 0; b < 2; ++b)
; #pragma unroll
;             for (int m = 0; m < 4; ++m)
; #pragma unroll
;                 for (int n = 0; n < 2; ++n) acc[a][b][m][n] = (f32x4){0.f, 0.f, 0.f, 0.f};
;     bf16x8 At[4][2], B0[2][2], B1[2][2];
;     const char* cA = (const char*)g.A + (size_t)cur.pm * tstepA + (size_t)cur.ko * 2; const char* cB = (const char*)g.Bt + (size_t)cur.pn * tstepB + (size_t)cur.ko * 2;
;     S.a_ready(cur);
;     if constexpr (SP2) {
;         PG8_STAGE(PG8_SB(0, 0), cB, voffB); PG8_STAGE(PG8_SB(0, 1), cB + hstepB, voffB); PG8_STAGE(PG8_SA(0, 0), cA, voffA); PG8_STAGE(PG8_SA(0, 1), cA + hstepA, voffA);
;         if (wr == 1) PG8_BAR;
;         PG8_WAIT_V(2); PG8_BAR;
;         PG8_STAGE(PG8_SB(1, 0), cB + kstep, voffB); PG8_STAGE(PG8_SA(1, 0), cA + kstep, voffA); PG8_STAGE(PG8_SB(1, 1), cB + hstepB + kstep, voffB);
;         PG8_WAIT_V(6); PG8_BAR;
;     } else {
;         PG8_STAGE(PG8_SB(0, 0), cB, voffB); PG8_STAGE(PG8_SA(0, 0), cA, voffA); PG8_STAGE(PG8_SB(0, 1), cB + hstepB, voffB); PG8_STAGE(PG8_SA(0, 1), cA + hstepA, voffA);
;         if (wr == 1) PG8_BAR;
;         PG8_WAIT_V(4); PG8_BAR;
;         PG8_STAGE(PG8_SB(1, 0), cB + kstep, voffB); PG8_STAGE(PG8_SA(1, 0), cA + kstep, voffA); PG8_STAGE(PG8_SB(1, 1), cB + hstepB + kstep, voffB);
;         PG8_WAIT_V(6); PG8_BAR;
;     }
.LBB0_320:
	s_or_b64 exec, exec, s[36:37]
	v_readlane_b32 s4, v254, 45
	v_readlane_b32 s5, v254, 46
	v_readlane_b32 s2, v254, 43
	s_xor_b64 s[6:7], s[4:5], -1
	s_mul_i32 s4, s2, 0x16800
	s_mov_b32 s5, s41
	v_writelane_b32 v254, s4, 56
	s_waitcnt lgkmcnt(0)
	s_barrier
	v_writelane_b32 v254, s5, 57
	v_writelane_b32 v254, s6, 58
	s_mov_b64 s[4:5], -1
	s_and_b64 vcc, exec, s[6:7]
	v_writelane_b32 v254, s7, 59
	s_cbranch_vccz .LBB0_373
	v_readlane_b32 s2, v254, 49
	v_readlane_b32 s5, v254, 32
	s_nop 1
	v_writelane_b32 v255, s5, 17
	s_and_b32 s4, s2, 7
	s_lshl_b32 s4, s4, 3
	s_lshr_b32 s5, s2, 6
	s_add_i32 s4, s4, s5
	s_lshl_b32 s4, s4, 8
	s_bfe_u32 s5, s2, 0x30003
	s_or_b32 s4, s4, s5
	s_or_b32 s4, s4, 0x80580000
	v_writelane_b32 v254, s4, 32
	s_nop 0
	v_readlane_b32 s2, v254, 32
	s_mov_b64 s[4:5], s[96:97]
	s_mov_b32 s20, s94
	s_mov_b32 s8, s94
	s_cmp_gt_i32 s2, -1
	v_mbcnt_lo_u32_b32 v0, -1, 0
	v_mbcnt_hi_u32_b32 v0, -1, v0
	s_cbranch_scc1 .LBB0_372
	s_load_dwordx2 s[6:7], s[4:5], 0xb8
	v_readlane_b32 s2, v254, 43
	s_mul_i32 s2, s2, 0x99c0000
	v_mov_b32_e32 v7, 1
	v_readlane_b32 s24, v254, 30
	s_waitcnt lgkmcnt(0)
	s_add_u32 s2, s6, s2
	s_addc_u32 s9, s7, 0
	s_add_u32 s42, s6, 0xd26f000
	s_addc_u32 s43, s7, 0
	s_add_u32 s44, s2, 0x2b20f000
	s_addc_u32 s45, s9, 0
	s_lshl_b32 s2, s8, 10
	v_lshl_add_u32 v1, v0, 4, s2
	v_ashrrev_i32_e32 v2, 31, v1
	v_lshrrev_b32_e32 v2, 22, v2
	v_add_u32_e32 v2, v1, v2
	v_ashrrev_i32_e32 v2, 10, v2
	v_mul_i32_i24_e32 v3, 0x400, v2
	v_sub_u32_e32 v3, v1, v3
	v_lshrrev_b32_e32 v4, 4, v3
	v_bitop3_b32 v3, v4, v3, 32 bitop3:0x6c
	v_ashrrev_i32_e32 v5, 31, v3
	v_lshrrev_b32_e32 v5, 26, v5
	v_add_u32_e32 v5, v3, v5
	v_lshlrev_b32_e32 v4, 3, v2
	v_ashrrev_i32_e32 v6, 6, v5
	v_and_b32_e32 v5, 0xc0, v5
	v_and_b32_e32 v4, -16, v4
	v_lshlrev_b32_e32 v2, 5, v2
	v_sub_u32_e32 v3, v3, v5
	v_add_u32_e32 v4, v6, v4
	v_and_b32_e32 v2, 32, v2
	v_ashrrev_i16_sdwa v3, v7, sext(v3) dst_sel:DWORD dst_unused:UNUSED_PAD src0_sel:DWORD src1_sel:BYTE_0
	v_add_u32_sdwa v2, v2, sext(v3) dst_sel:DWORD dst_unused:UNUSED_PAD src0_sel:DWORD src1_sel:WORD_0
	v_lshlrev_b32_e32 v3, 1, v4
	v_lshrrev_b32_e32 v5, 2, v4
	v_and_b32_e32 v6, 3, v6
	s_mov_b32 s2, 0x7fffe0
	v_and_b32_e32 v3, 24, v3
	v_and_b32_e32 v5, 4, v5
	v_and_or_b32 v6, v4, s2, v6
	v_or3_b32 v3, v6, v5, v3
	s_movk_i32 s8, 0x1600
	v_mul_lo_u32 v4, v4, s8
	v_mul_u32_u24_e32 v3, 0x1600, v3
	v_add_u32_e32 v1, 0x2000, v1
	v_add_lshl_u32 v208, v2, v4, 1
	v_add_lshl_u32 v209, v3, v2, 1
	v_ashrrev_i32_e32 v2, 31, v1
	v_lshrrev_b32_e32 v2, 22, v2
	v_add_u32_e32 v2, v1, v2
	v_ashrrev_i32_e32 v2, 10, v2
	v_mul_i32_i24_e32 v3, 0x400, v2
	v_sub_u32_e32 v1, v1, v3
	v_lshrrev_b32_e32 v3, 4, v1
	v_bitop3_b32 v1, v3, v1, 32 bitop3:0x6c
	v_ashrrev_i32_e32 v4, 31, v1
	v_lshrrev_b32_e32 v4, 26, v4
	v_add_u32_e32 v4, v1, v4
	v_ashrrev_i32_e32 v5, 6, v4
	v_and_b32_e32 v4, 0xffc0, v4
	v_lshlrev_b32_e32 v3, 3, v2
	v_sub_u32_e32 v1, v1, v4
	v_and_b32_e32 v3, -16, v3
	v_lshrrev_b16_e32 v4, 7, v1
	v_add_u32_e32 v3, v5, v3
	v_and_b32_e32 v4, 1, v4
	v_and_b32_e32 v5, 3, v5
	v_lshlrev_b32_e32 v2, 5, v2
	v_add_u16_e32 v1, v1, v4
	v_and_or_b32 v5, v3, s2, v5
	v_readlane_b32 s2, v254, 32
	v_readlane_b32 s25, v254, 31
	v_and_b32_e32 v2, 32, v2
	v_ashrrev_i16_sdwa v1, v7, sext(v1) dst_sel:DWORD dst_unused:UNUSED_PAD src0_sel:DWORD src1_sel:BYTE_0
	s_lshl_b32 s46, s20, 10
	s_and_b32 s96, s2, 0xff
	s_ashr_i32 s25, s24, 31
	v_add_u32_sdwa v1, v2, sext(v1) dst_sel:DWORD dst_unused:UNUSED_PAD src0_sel:DWORD src1_sel:WORD_0
	v_lshlrev_b32_e32 v2, 1, v3
	v_lshrrev_b32_e32 v4, 2, v3
	v_mul_lo_u32 v3, v3, s8
	s_ashr_i32 s22, s20, 2
	s_add_i32 s46, s46, 0
	s_bfe_u32 s33, s2, 0x80008
	s_lshl_b64 s[8:9], s[24:25], 1
	s_mul_i32 s10, s96, 0x2c0000
	s_add_u32 s10, s44, s10
	s_addc_u32 s11, s45, 0
	s_add_u32 s28, s10, s8
	s_mul_i32 s2, s33, 0x2c0000
	s_addc_u32 s29, s11, s9
	s_add_i32 s47, s46, 0x10000
	s_add_i32 s48, s46, 0x12000
	v_and_b32_e32 v2, 24, v2
	v_and_b32_e32 v4, 4, v4
	s_add_u32 s2, s42, s2
	v_or3_b32 v2, v5, v4, v2
	s_addc_u32 s10, s43, 0
	s_add_i32 s49, s46, 0x14000
	s_load_dwordx2 s[4:5], s[4:5], 0x30
	v_mul_u32_u24_e32 v2, 0x1600, v2
	s_mov_b32 m0, s47
	s_nop 0
	global_load_lds_dwordx4 v209, s[28:29]
	s_add_u32 s18, s28, 0x160000
	v_add_lshl_u32 v211, v2, v1, 1
	s_mov_b32 m0, s48
	s_nop 0
	global_load_lds_dwordx4 v211, s[28:29]
	s_addc_u32 s19, s29, 0
	s_add_i32 s50, s46, 0x16000
	s_mov_b32 m0, s49
	s_nop 0
	global_load_lds_dwordx4 v209, s[18:19]
	s_add_u32 s30, s2, s8
	s_mov_b32 m0, s50
	s_nop 0
	global_load_lds_dwordx4 v211, s[18:19]
	s_addc_u32 s31, s10, s9
	s_add_i32 s51, s46, 0x2000
	s_add_i32 s52, s46, 0x4000
	s_mov_b32 m0, s46
	s_nop 0
	global_load_lds_dwordx4 v208, s[30:31]
	s_add_u32 s8, s30, 0x160000
	v_add_lshl_u32 v210, v1, v3, 1
	s_mov_b32 m0, s51
	s_nop 0
	global_load_lds_dwordx4 v210, s[30:31]
	s_addc_u32 s9, s31, 0
	s_add_i32 s53, s46, 0x6000
	s_mov_b32 m0, s52
	s_nop 0
	global_load_lds_dwordx4 v208, s[8:9]
	s_cmp_eq_u32 s22, 1
	s_mov_b32 m0, s53
	s_nop 0
	global_load_lds_dwordx4 v210, s[8:9]
	s_cselect_b64 s[8:9], -1, 0
	v_writelane_b32 v254, s8, 60
	v_mov_b32_e32 v243, 1
	s_cmp_lg_u32 s22, 1
	v_writelane_b32 v254, s9, 61
	s_cbranch_scc1 .LBB0_324
	s_barrier

;     __host__ __device__ __forceinline__ bool next(int i, Unit& u) const {
;     ...
;         int wgid = (int)L; { const int q = nwg / NXCD, r = nwg % NXCD, xcd = wgid % NXCD, off = wgid / NXCD; wgid = (xcd < r ? xcd * (q + 1) : r * (q + 1) + (xcd - r) * q) + off; }
;         const int nig = WGM * nN, gid = wgid / nig, fm = gid * WGM, gsz = (nM - fm) < WGM ? (nM - fm) : WGM;
;         u.pm = fm + ((wgid % nig) % gsz); u.pn = (wgid % nig) / gsz; u.ko = 0; u.nk = nk; return true;
.LBB0_337:
	s_ashr_i32 s2, s7, 3
	s_add_i32 s2, s26, s2
	s_ashr_i32 s7, s2, 31
	s_lshr_b32 s7, s7, 26
	s_add_i32 s7, s2, s7
	s_ashr_i32 s8, s7, 6
	s_lshl_b32 s8, s8, 3
	s_sub_i32 s9, 64, s8
	s_min_i32 s9, s9, 8
	s_abs_i32 s23, s9
	v_cvt_f32_u32_e32 v0, s23
	s_sub_i32 s25, 0, s23
	s_andn2_b32 s7, s7, 63
	s_sub_i32 s2, s2, s7
	v_rcp_iflag_f32_e32 v0, v0
	s_abs_i32 s7, s2
	s_xor_b32 s24, s2, s9
	s_ashr_i32 s24, s24, 31
	v_mul_f32_e32 v0, 0x4f7ffffe, v0
	v_cvt_u32_f32_e32 v0, v0
	s_nop 0
	v_readfirstlane_b32 s26, v0
	s_mul_i32 s25, s25, s26
	s_mul_hi_u32 s25, s26, s25
	s_add_i32 s26, s26, s25
	s_mul_hi_u32 s25, s7, s26
	s_mul_i32 s26, s25, s23
	s_sub_i32 s7, s7, s26
	s_add_i32 s27, s25, 1
	s_sub_i32 s26, s7, s23
	s_cmp_ge_u32 s7, s23
	s_cselect_b32 s25, s27, s25
	s_cselect_b32 s7, s26, s7
	s_add_i32 s26, s25, 1
	s_cmp_ge_u32 s7, s23
	s_cselect_b32 s7, s26, s25
	s_xor_b32 s7, s7, s24
	s_sub_i32 s7, s7, s24
	s_mul_i32 s9, s7, s9
	s_sub_i32 s2, s2, s9
	s_add_i32 s8, s8, s7
	s_lshl_b32 s8, s8, 8
	s_or_b32 s2, s2, s8
	s_or_b32 s7, s2, 0x80580000

; #define PG8_WAIT_V(n) asm volatile("s_waitcnt vmcnt(" #n ")" ::: "memory")
; #define PG8_BAR __builtin_amdgcn_s_barrier()
; template <class Epi, class Sched, bool ALIGN_EPI = false, bool SP2 = false>
; __device__ __forceinline__ void gemm_phase(PG8_LAS unsigned char* lds, const Gemm g, const Sched& S, const Epi& E, const int wv) {
;     ...
;         cur = nxt; cA = nA; cB = nB; ++ui;
;         if constexpr (ALIGN_EPI) { if (wr == 1) PG8_BAR; }
;     }
;     PG8_WAIT_V(0);
;     if constexpr (!ALIGN_EPI) { if (wr == 0) PG8_BAR; }
;     PG8_BAR;
.LBB0_371:
	v_readlane_b32 s97, v255, 17
	s_nop 1
	v_writelane_b32 v254, s97, 32
	s_waitcnt vmcnt(0)
	v_readlane_b32 s96, v254, 47
	v_readlane_b32 s97, v254, 48
	v_readlane_b32 s92, v254, 49
	v_readlane_b32 s90, v254, 52
	s_barrier
	v_readlane_b32 s93, v254, 50
